# nt cache policy on read-once/write-once streams: hgrn_sample state loads+stores, final LayerNorm loads+stores
# speedup vs baseline: 1.0067x; 1.0033x over previous
.Lhs_ld1:
	s_or_b64 exec, exec, s[10:11]
	s_add_i32 s6, s6, s3
	s_ashr_i32 s7, s6, 31
	v_lshl_add_u64 v[90:91], s[8:9], 1, v[4:5]
	s_lshl_b64 s[6:7], s[6:7], 19
	s_lshl_b32 s8, s13, 16
	s_or_b32 s6, s6, s8
	v_lshl_add_u64 v[32:33], v[6:7], 0, s[6:7]
	v_lshl_add_u64 v[30:31], v[8:9], 0, s[6:7]
	global_load_dwordx2 v[90:91], v[90:91], off
	v_lshl_add_u64 v[42:43], v[32:33], 0, v[12:13]
	global_load_dwordx4 v[100:103], v[42:43], off nt
	v_lshl_add_u64 v[44:45], v[32:33], 0, v[14:15]
	global_load_dwordx4 v[104:107], v[44:45], off nt
	v_lshl_add_u64 v[46:47], v[32:33], 0, v[16:17]
	global_load_dwordx4 v[108:111], v[46:47], off nt
	v_lshl_add_u64 v[48:49], v[32:33], 0, v[18:19]
	global_load_dwordx4 v[112:115], v[48:49], off nt
	v_lshl_add_u64 v[50:51], v[32:33], 0, v[20:21]
	global_load_dwordx4 v[116:119], v[50:51], off nt
	v_lshl_add_u64 v[52:53], v[32:33], 0, v[22:23]
	global_load_dwordx4 v[120:123], v[52:53], off nt
	v_lshl_add_u64 v[54:55], v[32:33], 0, v[24:25]
	global_load_dwordx4 v[124:127], v[54:55], off nt
	v_lshl_add_u64 v[56:57], v[32:33], 0, v[26:27]
	global_load_dwordx4 v[128:131], v[56:57], off nt
	s_and_saveexec_b64 s[10:11], vcc
	s_cbranch_execz .Lhs_w1
	s_waitcnt vmcnt(9)
	v_lshlrev_b32_e32 v70, 16, v70
	v_lshlrev_b32_e32 v71, 16, v71
	ds_write2st64_b32 v1, v70, v71 offset1:2
.Lhs_w1:
	s_or_b64 exec, exec, s[10:11]
	s_waitcnt lgkmcnt(0)
	s_barrier
	ds_read_b32 v132, v34 offset:512
	ds_read_b32 v134, v34
	ds_read_b32 v136, v34 offset:576
	ds_read_b32 v138, v34 offset:64
	ds_read_b32 v140, v34 offset:640
	ds_read_b32 v142, v34 offset:128
	ds_read_b32 v144, v34 offset:704
	ds_read_b32 v146, v34 offset:192
	s_waitcnt lgkmcnt(7)
	ds_read_b32 v148, v34 offset:768
	ds_read_b32 v150, v34 offset:256
	ds_read_b32 v152, v34 offset:832
	ds_read_b32 v154, v34 offset:320
	ds_read_b32 v156, v34 offset:896
	ds_read_b32 v158, v34 offset:384
	ds_read_b32 v160, v34 offset:960
	ds_read_b32 v162, v34 offset:448
	s_waitcnt vmcnt(8)
	v_lshlrev_b32_e32 v37, 16, v90
	v_and_b32_e32 v39, 0xffff0000, v90
	v_lshlrev_b32_e32 v38, 16, v91
	v_and_b32_e32 v40, 0xffff0000, v91
	s_waitcnt lgkmcnt(0)
	s_waitcnt vmcnt(7)
	v_sub_f32_e32 v73, v39, v101
	v_sub_f32_e32 v72, v37, v100
	v_sub_f32_e32 v75, v40, v103
	v_sub_f32_e32 v74, v38, v102
	v_pk_fma_f32 v[102:103], v[74:75], v[132:133], v[102:103] op_sel_hi:[1,0,1]
	v_pk_fma_f32 v[100:101], v[72:73], v[132:133], v[100:101] op_sel_hi:[1,0,1]
	v_lshl_add_u64 v[42:43], v[30:31], 0, v[12:13]
	global_store_dwordx4 v[42:43], v[100:103], off nt
	v_pk_fma_f32 v[76:77], v[100:101], v[134:135], 0 op_sel_hi:[1,0,0]
	v_pk_fma_f32 v[78:79], v[102:103], v[134:135], 0 op_sel_hi:[1,0,0]
	s_waitcnt vmcnt(7)
	v_sub_f32_e32 v73, v39, v105
	v_sub_f32_e32 v72, v37, v104
	v_sub_f32_e32 v75, v40, v107
	v_sub_f32_e32 v74, v38, v106
	v_pk_fma_f32 v[106:107], v[74:75], v[136:137], v[106:107] op_sel_hi:[1,0,1]
	v_pk_fma_f32 v[104:105], v[72:73], v[136:137], v[104:105] op_sel_hi:[1,0,1]
	v_lshl_add_u64 v[44:45], v[30:31], 0, v[14:15]
	global_store_dwordx4 v[44:45], v[104:107], off nt
	v_pk_fma_f32 v[78:79], v[106:107], v[138:139], v[78:79] op_sel_hi:[1,0,1]
	v_pk_fma_f32 v[76:77], v[104:105], v[138:139], v[76:77] op_sel_hi:[1,0,1]
	s_waitcnt vmcnt(7)
	v_sub_f32_e32 v73, v39, v109
	v_sub_f32_e32 v72, v37, v108
	v_sub_f32_e32 v75, v40, v111
	v_sub_f32_e32 v74, v38, v110
	v_pk_fma_f32 v[110:111], v[74:75], v[140:141], v[110:111] op_sel_hi:[1,0,1]
	v_pk_fma_f32 v[108:109], v[72:73], v[140:141], v[108:109] op_sel_hi:[1,0,1]
	v_lshl_add_u64 v[46:47], v[30:31], 0, v[16:17]
	global_store_dwordx4 v[46:47], v[108:111], off nt
	v_pk_fma_f32 v[78:79], v[110:111], v[142:143], v[78:79] op_sel_hi:[1,0,1]
	v_pk_fma_f32 v[76:77], v[108:109], v[142:143], v[76:77] op_sel_hi:[1,0,1]
	s_waitcnt vmcnt(7)
	v_sub_f32_e32 v73, v39, v113
	v_sub_f32_e32 v72, v37, v112
	v_sub_f32_e32 v75, v40, v115
	v_sub_f32_e32 v74, v38, v114
	v_pk_fma_f32 v[114:115], v[74:75], v[144:145], v[114:115] op_sel_hi:[1,0,1]
	v_pk_fma_f32 v[112:113], v[72:73], v[144:145], v[112:113] op_sel_hi:[1,0,1]
	v_lshl_add_u64 v[48:49], v[30:31], 0, v[18:19]
	global_store_dwordx4 v[48:49], v[112:115], off nt
	v_pk_fma_f32 v[78:79], v[114:115], v[146:147], v[78:79] op_sel_hi:[1,0,1]
	v_pk_fma_f32 v[76:77], v[112:113], v[146:147], v[76:77] op_sel_hi:[1,0,1]
	s_waitcnt vmcnt(7)
	v_sub_f32_e32 v73, v39, v117
	v_sub_f32_e32 v72, v37, v116
	v_sub_f32_e32 v75, v40, v119
	v_sub_f32_e32 v74, v38, v118
	v_pk_fma_f32 v[118:119], v[74:75], v[148:149], v[118:119] op_sel_hi:[1,0,1]
	v_pk_fma_f32 v[116:117], v[72:73], v[148:149], v[116:117] op_sel_hi:[1,0,1]
	v_lshl_add_u64 v[50:51], v[30:31], 0, v[20:21]
	global_store_dwordx4 v[50:51], v[116:119], off nt
	v_pk_fma_f32 v[78:79], v[118:119], v[150:151], v[78:79] op_sel_hi:[1,0,1]
	v_pk_fma_f32 v[76:77], v[116:117], v[150:151], v[76:77] op_sel_hi:[1,0,1]
	s_waitcnt vmcnt(7)
	v_sub_f32_e32 v73, v39, v121
	v_sub_f32_e32 v72, v37, v120
	v_sub_f32_e32 v75, v40, v123
	v_sub_f32_e32 v74, v38, v122
	v_pk_fma_f32 v[122:123], v[74:75], v[152:153], v[122:123] op_sel_hi:[1,0,1]
	v_pk_fma_f32 v[120:121], v[72:73], v[152:153], v[120:121] op_sel_hi:[1,0,1]
	v_lshl_add_u64 v[52:53], v[30:31], 0, v[22:23]
	global_store_dwordx4 v[52:53], v[120:123], off nt
	v_pk_fma_f32 v[78:79], v[122:123], v[154:155], v[78:79] op_sel_hi:[1,0,1]
	v_pk_fma_f32 v[76:77], v[120:121], v[154:155], v[76:77] op_sel_hi:[1,0,1]
	s_waitcnt vmcnt(7)
	v_sub_f32_e32 v73, v39, v125
	v_sub_f32_e32 v72, v37, v124
	v_sub_f32_e32 v75, v40, v127
	v_sub_f32_e32 v74, v38, v126
	v_pk_fma_f32 v[126:127], v[74:75], v[156:157], v[126:127] op_sel_hi:[1,0,1]
	v_pk_fma_f32 v[124:125], v[72:73], v[156:157], v[124:125] op_sel_hi:[1,0,1]
	v_lshl_add_u64 v[54:55], v[30:31], 0, v[24:25]
	global_store_dwordx4 v[54:55], v[124:127], off nt
	v_pk_fma_f32 v[78:79], v[126:127], v[158:159], v[78:79] op_sel_hi:[1,0,1]
	v_pk_fma_f32 v[76:77], v[124:125], v[158:159], v[76:77] op_sel_hi:[1,0,1]
	s_waitcnt vmcnt(7)
	v_sub_f32_e32 v73, v39, v129
	v_sub_f32_e32 v72, v37, v128
	v_sub_f32_e32 v75, v40, v131
	v_sub_f32_e32 v74, v38, v130
	v_pk_fma_f32 v[130:131], v[74:75], v[160:161], v[130:131] op_sel_hi:[1,0,1]
	v_pk_fma_f32 v[128:129], v[72:73], v[160:161], v[128:129] op_sel_hi:[1,0,1]
	v_lshl_add_u64 v[56:57], v[30:31], 0, v[26:27]
	global_store_dwordx4 v[56:57], v[128:131], off nt
	v_pk_fma_f32 v[78:79], v[130:131], v[162:163], v[78:79] op_sel_hi:[1,0,1]
	v_pk_fma_f32 v[76:77], v[128:129], v[162:163], v[76:77] op_sel_hi:[1,0,1]
	ds_write_b128 v35, v[76:79] offset:1024
	v_mov_b32_e32 v30, 0
	s_waitcnt lgkmcnt(0)
	s_barrier
	s_and_saveexec_b64 s[8:9], vcc
	s_cbranch_execz .LBB0_980
	ds_read2st64_b32 v[30:31], v1 offset0:4 offset1:6
	v_xor_b32_e32 v33, 1, v216
	s_waitcnt lgkmcnt(0)
	v_add_f32_e32 v30, 0, v30
	v_add_f32_e32 v32, v30, v31
	ds_read2st64_b32 v[30:31], v1 offset0:8 offset1:10
	s_waitcnt lgkmcnt(0)
	v_add_f32_e32 v30, v32, v30
	v_add_f32_e32 v32, v30, v31
	ds_read2st64_b32 v[30:31], v1 offset0:12 offset1:14
	s_waitcnt lgkmcnt(0)
	v_add_f32_e32 v30, v32, v30
	v_add_f32_e32 v32, v30, v31
	ds_read2st64_b32 v[30:31], v1 offset0:16 offset1:18
	s_waitcnt lgkmcnt(0)
	v_add_f32_e32 v30, v32, v30
	v_add_f32_e32 v32, v30, v31
	ds_read2st64_b32 v[30:31], v1 offset0:20 offset1:22
	s_waitcnt lgkmcnt(0)
	v_add_f32_e32 v30, v32, v30
	v_add_f32_e32 v32, v30, v31
	ds_read2st64_b32 v[30:31], v1 offset0:24 offset1:26
	s_waitcnt lgkmcnt(0)
	v_add_f32_e32 v30, v32, v30
	v_add_f32_e32 v32, v30, v31
	ds_read2st64_b32 v[30:31], v1 offset0:28 offset1:30
	s_waitcnt lgkmcnt(0)
	v_add_f32_e32 v30, v32, v30
	v_add_f32_e32 v32, v30, v31
	ds_read2st64_b32 v[30:31], v1 offset0:32 offset1:34
	s_waitcnt lgkmcnt(0)
	v_add_f32_e32 v30, v32, v30
	v_and_b32_e32 v32, 64, v216
	v_add_u32_e32 v32, 64, v32
	v_cmp_lt_i32_e64 s[6:7], v33, v32
	v_add_f32_e32 v30, v30, v31
	v_mul_f32_e32 v31, v30, v30
	v_cndmask_b32_e64 v33, v216, v33, s[6:7]
	v_lshlrev_b32_e32 v33, 2, v33
	ds_bpermute_b32 v31, v33, v31
	v_xor_b32_e32 v33, 2, v216
	v_cmp_lt_i32_e64 s[6:7], v33, v32
	s_waitcnt lgkmcnt(0)
	v_fmac_f32_e32 v31, v30, v30
	v_cndmask_b32_e64 v33, v216, v33, s[6:7]
	v_lshlrev_b32_e32 v33, 2, v33
	ds_bpermute_b32 v33, v33, v31
	s_waitcnt lgkmcnt(0)
	v_add_f32_e32 v31, v31, v33
	v_xor_b32_e32 v33, 4, v216
	v_cmp_lt_i32_e64 s[6:7], v33, v32
	s_nop 1
	v_cndmask_b32_e64 v33, v216, v33, s[6:7]
	v_lshlrev_b32_e32 v33, 2, v33
	ds_bpermute_b32 v33, v33, v31
	s_waitcnt lgkmcnt(0)
	v_add_f32_e32 v31, v31, v33
	v_xor_b32_e32 v33, 8, v216
	v_cmp_lt_i32_e64 s[6:7], v33, v32
	s_nop 1
	v_cndmask_b32_e64 v33, v216, v33, s[6:7]
	v_lshlrev_b32_e32 v33, 2, v33
	ds_bpermute_b32 v33, v33, v31
	s_waitcnt lgkmcnt(0)
	v_add_f32_e32 v31, v31, v33
	v_xor_b32_e32 v33, 16, v216
	v_cmp_lt_i32_e64 s[6:7], v33, v32
	s_nop 1
	v_cndmask_b32_e64 v33, v216, v33, s[6:7]
	v_lshlrev_b32_e32 v33, 2, v33
	ds_bpermute_b32 v33, v33, v31
	s_waitcnt lgkmcnt(0)
	v_add_f32_e32 v31, v31, v33
	v_xor_b32_e32 v33, 32, v216
	v_cmp_lt_i32_e64 s[6:7], v33, v32
	s_nop 1
	v_cndmask_b32_e64 v32, v216, v33, s[6:7]
	v_lshlrev_b32_e32 v32, 2, v32
	ds_bpermute_b32 v32, v32, v31
	s_and_saveexec_b64 s[6:7], s[4:5]
	s_cbranch_execz .LBB0_979
	s_waitcnt lgkmcnt(0)
	v_add_f32_e32 v31, v31, v32
	ds_write_b32 v36, v31 offset:9216

.LBB0_1286:
	v_ashrrev_i32_e32 v33, 31, v32
	v_lshlrev_b64 v[40:41], 7, v[32:33]
	v_lshl_add_u64 v[40:41], v[34:35], 0, v[40:41]
	v_lshlrev_b64 v[46:47], 11, v[32:33]
	global_load_dwordx2 v[62:63], v[40:41], off nt
	v_lshl_add_u64 v[40:41], v[38:39], 0, v[46:47]
	global_load_dwordx4 v[46:49], v[40:41], off nt
	global_load_dwordx4 v[50:53], v[40:41], off offset:1024 nt
	v_add_u32_e32 v40, 1, v32
	v_ashrrev_i32_e32 v41, 31, v40
	v_lshlrev_b64 v[54:55], 7, v[40:41]
	v_lshl_add_u64 v[54:55], v[34:35], 0, v[54:55]
	global_load_dwordx2 v[64:65], v[54:55], off nt
	v_lshlrev_b64 v[56:57], 11, v[40:41]
	v_lshl_add_u64 v[58:59], v[38:39], 0, v[56:57]
	global_load_dwordx4 v[54:57], v[58:59], off nt
	v_lshlrev_b64 v[60:61], 12, v[32:33]
	v_lshl_add_u64 v[70:71], v[36:37], 0, v[60:61]
	global_load_dwordx4 v[58:61], v[58:59], off offset:1024 nt
	v_lshlrev_b64 v[40:41], 12, v[40:41]
	v_lshl_add_u64 v[40:41], v[36:37], 0, v[40:41]
	v_add_u32_e32 v32, s95, v32
	s_waitcnt vmcnt(0)
	ds_bpermute_b32 v66, v42, v62
	ds_bpermute_b32 v67, v42, v63
	v_lshlrev_b32_e32 v33, 16, v46
	v_and_b32_e32 v68, 0xffff0000, v46
	v_lshlrev_b32_e32 v69, 16, v47
	v_and_b32_e32 v72, 0xffff0000, v47
	v_lshlrev_b32_e32 v73, 16, v48
	ds_bpermute_b32 v46, v42, v64
	ds_bpermute_b32 v47, v42, v65
	v_and_b32_e32 v74, 0xffff0000, v48
	v_lshlrev_b32_e32 v75, 16, v49
	v_and_b32_e32 v76, 0xffff0000, v49
	s_waitcnt lgkmcnt(2)
	v_pk_add_f32 v[48:49], v[62:63], v[66:67]
	v_lshlrev_b32_e32 v77, 16, v50
	v_and_b32_e32 v78, 0xffff0000, v50
	v_lshlrev_b32_e32 v79, 16, v51
	v_and_b32_e32 v80, 0xffff0000, v51
	ds_bpermute_b32 v50, v43, v48
	ds_bpermute_b32 v51, v43, v49
	s_waitcnt lgkmcnt(2)
	v_pk_add_f32 v[46:47], v[64:65], v[46:47]
	v_lshlrev_b32_e32 v81, 16, v52
	v_and_b32_e32 v82, 0xffff0000, v52
	v_lshlrev_b32_e32 v83, 16, v53
	v_and_b32_e32 v84, 0xffff0000, v53
	ds_bpermute_b32 v52, v43, v46
	ds_bpermute_b32 v53, v43, v47
	s_waitcnt lgkmcnt(2)
	v_pk_add_f32 v[48:49], v[48:49], v[50:51]
	ds_bpermute_b32 v50, v44, v48
	ds_bpermute_b32 v51, v44, v49
	v_lshlrev_b32_e32 v89, 16, v56
	s_waitcnt lgkmcnt(2)
	v_pk_add_f32 v[46:47], v[46:47], v[52:53]
	ds_bpermute_b32 v52, v44, v46
	ds_bpermute_b32 v53, v44, v47
	s_waitcnt lgkmcnt(2)
	v_pk_add_f32 v[48:49], v[48:49], v[50:51]
	ds_bpermute_b32 v50, v45, v48
	ds_bpermute_b32 v51, v45, v49
	v_and_b32_e32 v90, 0xffff0000, v56
	s_waitcnt lgkmcnt(2)
	v_pk_add_f32 v[46:47], v[46:47], v[52:53]
	ds_bpermute_b32 v52, v45, v46
	ds_bpermute_b32 v53, v45, v47
	s_waitcnt lgkmcnt(2)
	v_pk_add_f32 v[48:49], v[48:49], v[50:51]
	v_lshlrev_b32_e32 v85, 16, v54
	v_pk_mul_f32 v[48:49], v[48:49], s[4:5] op_sel_hi:[1,0]
	v_and_b32_e32 v86, 0xffff0000, v54
	s_waitcnt lgkmcnt(0)
	v_pk_add_f32 v[46:47], v[46:47], v[52:53]
	v_fma_f32 v56, -v48, v48, v49
	v_sub_f32_e32 v51, v72, v48
	v_sub_f32_e32 v52, v33, v48
	v_sub_f32_e32 v62, v73, v48
	v_pk_mul_f32 v[72:73], v[46:47], s[4:5] op_sel_hi:[1,0]
	v_max_f32_e32 v33, 0, v56
	v_fma_f32 v46, -v72, v72, v73
	v_add_f32_e32 v33, 0x3727c5ac, v33
	v_max_f32_e32 v46, 0, v46
	v_mul_f32_e32 v47, 0x4b800000, v33
	v_cmp_gt_f32_e32 vcc, s5, v33
	v_add_f32_e32 v46, 0x3727c5ac, v46
	v_cmp_gt_f32_e64 s[0:1], s5, v46
	v_cndmask_b32_e32 v33, v33, v47, vcc
	v_mul_f32_e32 v47, 0x4b800000, v46
	v_rsq_f32_e32 v33, v33
	v_cndmask_b32_e64 v46, v46, v47, s[0:1]
	v_rsq_f32_e32 v47, v46
	v_sub_f32_e32 v50, v69, v48
	v_mul_f32_e32 v46, 0x45800000, v33
	v_sub_f32_e32 v53, v68, v48
	v_cndmask_b32_e32 v46, v33, v46, vcc
	v_lshlrev_b32_e32 v87, 16, v55
	v_and_b32_e32 v88, 0xffff0000, v55
	v_sub_f32_e32 v55, v76, v48
	v_sub_f32_e32 v54, v75, v48
	v_sub_f32_e32 v63, v74, v48
	v_sub_f32_e32 v65, v80, v48
	v_sub_f32_e32 v64, v79, v48
	v_sub_f32_e32 v67, v78, v48
	v_sub_f32_e32 v66, v77, v48
	v_sub_f32_e32 v69, v84, v48
	v_sub_f32_e32 v68, v83, v48
	v_sub_f32_e32 v49, v82, v48
	v_sub_f32_e32 v48, v81, v48
	v_mul_f32_e32 v33, 0x45800000, v47
	v_pk_mul_f32 v[52:53], v[52:53], v[46:47] op_sel_hi:[1,0]
	v_pk_mul_f32 v[50:51], v[50:51], v[46:47] op_sel_hi:[1,0]
	v_pk_mul_f32 v[62:63], v[62:63], v[46:47] op_sel_hi:[1,0]
	v_pk_mul_f32 v[54:55], v[54:55], v[46:47] op_sel_hi:[1,0]
	v_pk_mul_f32 v[66:67], v[66:67], v[46:47] op_sel_hi:[1,0]
	v_pk_mul_f32 v[64:65], v[64:65], v[46:47] op_sel_hi:[1,0]
	v_pk_mul_f32 v[74:75], v[48:49], v[46:47] op_sel_hi:[1,0]
	v_pk_mul_f32 v[68:69], v[68:69], v[46:47] op_sel_hi:[1,0]
	v_cndmask_b32_e64 v56, v47, v33, s[0:1]
	v_pk_fma_f32 v[48:49], v[2:3], v[50:51], v[18:19]
	v_pk_fma_f32 v[46:47], v[0:1], v[52:53], v[16:17]
	v_lshlrev_b32_e32 v91, 16, v57
	v_pk_fma_f32 v[52:53], v[6:7], v[54:55], v[22:23]
	v_pk_fma_f32 v[50:51], v[4:5], v[62:63], v[20:21]
	v_pk_fma_f32 v[64:65], v[10:11], v[64:65], v[26:27]
	v_pk_fma_f32 v[62:63], v[8:9], v[66:67], v[24:25]
	v_pk_fma_f32 v[68:69], v[14:15], v[68:69], v[30:31]
	v_pk_fma_f32 v[66:67], v[12:13], v[74:75], v[28:29]
	global_store_dwordx4 v[70:71], v[46:49], off nt
	global_store_dwordx4 v[70:71], v[50:53], off offset:16 nt
	global_store_dwordx4 v[70:71], v[62:65], off offset:2048 nt
	global_store_dwordx4 v[70:71], v[66:69], off offset:2064 nt
	v_and_b32_e32 v33, 0xffff0000, v57
	v_lshlrev_b32_e32 v57, 16, v60
	v_sub_f32_e32 v47, v88, v72
	v_sub_f32_e32 v46, v87, v72
	v_sub_f32_e32 v49, v86, v72
	v_sub_f32_e32 v48, v85, v72
	v_pk_mul_f32 v[50:51], v[48:49], v[56:57] op_sel_hi:[1,0]
	v_pk_mul_f32 v[46:47], v[46:47], v[56:57] op_sel_hi:[1,0]
	v_lshlrev_b32_e32 v52, 16, v58
	v_pk_fma_f32 v[48:49], v[2:3], v[46:47], v[18:19]
	v_pk_fma_f32 v[46:47], v[0:1], v[50:51], v[16:17]
	global_store_dwordx4 v[40:41], v[46:49], off nt
	v_and_b32_e32 v53, 0xffff0000, v58
	v_lshlrev_b32_e32 v54, 16, v59
	v_sub_f32_e32 v47, v33, v72
	v_sub_f32_e32 v46, v91, v72
	v_sub_f32_e32 v49, v90, v72
	v_sub_f32_e32 v48, v89, v72
	v_pk_mul_f32 v[50:51], v[48:49], v[56:57] op_sel_hi:[1,0]
	v_pk_mul_f32 v[46:47], v[46:47], v[56:57] op_sel_hi:[1,0]
	v_and_b32_e32 v55, 0xffff0000, v59
	v_pk_fma_f32 v[48:49], v[6:7], v[46:47], v[22:23]
	v_pk_fma_f32 v[46:47], v[4:5], v[50:51], v[20:21]
	global_store_dwordx4 v[40:41], v[46:49], off offset:16 nt
	v_and_b32_e32 v58, 0xffff0000, v60
	v_lshlrev_b32_e32 v59, 16, v61
	v_sub_f32_e32 v47, v55, v72
	v_sub_f32_e32 v46, v54, v72
	v_sub_f32_e32 v49, v53, v72
	v_sub_f32_e32 v48, v52, v72
	v_pk_mul_f32 v[50:51], v[48:49], v[56:57] op_sel_hi:[1,0]
	v_pk_mul_f32 v[46:47], v[46:47], v[56:57] op_sel_hi:[1,0]
	v_and_b32_e32 v60, 0xffff0000, v61
	v_pk_fma_f32 v[48:49], v[10:11], v[46:47], v[26:27]
	v_pk_fma_f32 v[46:47], v[8:9], v[50:51], v[24:25]
	global_store_dwordx4 v[40:41], v[46:49], off offset:2048 nt
	v_cmp_lt_i32_e32 vcc, s6, v32
	s_or_b64 s[2:3], vcc, s[2:3]
	v_sub_f32_e32 v47, v60, v72
	v_sub_f32_e32 v46, v59, v72
	v_sub_f32_e32 v49, v58, v72
	v_sub_f32_e32 v48, v57, v72
	v_pk_mul_f32 v[50:51], v[48:49], v[56:57] op_sel_hi:[1,0]
	v_pk_mul_f32 v[46:47], v[46:47], v[56:57] op_sel_hi:[1,0]
	s_nop 0
	v_pk_fma_f32 v[48:49], v[14:15], v[46:47], v[30:31]
	v_pk_fma_f32 v[46:47], v[12:13], v[50:51], v[28:29]
	global_store_dwordx4 v[40:41], v[46:49], off offset:2064 nt
	s_andn2_b64 exec, exec, s[2:3]
	s_cbranch_execnz .LBB0_1286
